# MLA: next-tile K/V global loads issued by the staging half before the tile barrier (off the compute half's interval)
# speedup vs baseline: 1.0212x; 1.0157x over previous
.LBB0_1496:
	s_mov_b32 s56, 0x5040100
	s_mov_b32 s57, 0x7060302
	s_waitcnt vmcnt(4)
	ds_write_b128 v161, v[24:27]
	ds_write_b128 v162, v[28:31]
	ds_write_b128 v166, v[32:35]
	ds_write_b128 v167, v[36:39]
	ds_write_b128 v188, v[40:43]
	ds_write_b128 v211, v[48:51]
	s_waitcnt vmcnt(1)
	v_perm_b32 v108, v60, v52, s56
	v_perm_b32 v109, v60, v52, s57
	v_add_u32_e32 v110, 0x7000, v159
	ds_write2_b32 v110, v108, v109 offset1:72
	v_perm_b32 v108, v61, v53, s56
	v_perm_b32 v109, v61, v53, s57
	ds_write2_b32 v110, v108, v109 offset0:144 offset1:216
	v_perm_b32 v108, v62, v54, s56
	v_perm_b32 v109, v62, v54, s57
	v_add_u32_e32 v110, 0x7400, v159
	ds_write2_b32 v110, v108, v109 offset0:32 offset1:104
	v_perm_b32 v108, v63, v55, s56
	v_perm_b32 v109, v63, v55, s57
	ds_write2_b32 v110, v108, v109 offset0:176 offset1:248
	s_waitcnt vmcnt(0)
	v_perm_b32 v108, v64, v56, s56
	v_perm_b32 v109, v64, v56, s57
	v_add_u32_e32 v110, 0x9400, v159
	ds_write2_b32 v110, v108, v109 offset1:72
	v_perm_b32 v108, v65, v57, s56
	v_perm_b32 v109, v65, v57, s57
	ds_write2_b32 v110, v108, v109 offset0:144 offset1:216
	v_perm_b32 v108, v66, v58, s56
	v_perm_b32 v109, v66, v58, s57
	v_add_u32_e32 v110, 0x9800, v159
	ds_write2_b32 v110, v108, v109 offset0:32 offset1:104
	v_perm_b32 v108, v67, v59, s56
	v_perm_b32 v109, v67, v59, s57
	ds_write2_b32 v110, v108, v109 offset0:176 offset1:248
	s_mov_b64 s[20:21], -1
	s_mov_b64 s[16:17], 0
	s_cmp_lt_i32 s53, 33
	s_mov_b64 s[18:19], 0
	s_waitcnt lgkmcnt(0)
	s_cbranch_scc1 .Lmla_ld
	s_barrier
	s_branch .LBB0_1483
.Lmla_ld:
	s_cmp_lt_u32 s53, 2
	s_cbranch_scc1 .Lmla_ld_slow
	s_mov_b64 s[54:55], 0x20000
	v_lshl_add_u64 v[112:113], v[112:113], 0, v[114:115]
	v_lshl_add_u64 v[118:119], v[118:119], 0, v[120:121]
	v_lshl_add_u64 v[122:123], v[122:123], 0, v[124:125]
	v_lshl_add_u64 v[126:127], v[126:127], 0, v[134:135]
	v_lshl_add_u64 v[136:137], v[136:137], 0, v[144:145]
	v_lshl_add_u64 v[140:141], v[140:141], 0, v[208:209]
	v_lshl_add_u64 v[138:139], v[138:139], 0, s[54:55]
	v_lshl_add_u64 v[142:143], v[142:143], 0, s[54:55]
	global_load_dwordx4 v[24:27], v[112:113], off
	global_load_dwordx4 v[28:31], v[118:119], off
	global_load_dwordx4 v[32:35], v[122:123], off
	global_load_dwordx4 v[36:39], v[126:127], off
	global_load_dwordx4 v[40:43], v[136:137], off
	global_load_dwordx4 v[48:51], v[140:141], off
	global_load_dwordx4 v[52:55], v[138:139], off offset:128
	global_load_dwordx4 v[56:59], v[138:139], off offset:192
	global_load_dwordx4 v[60:63], v[142:143], off offset:128
	global_load_dwordx4 v[64:67], v[142:143], off offset:192
	s_barrier
	s_branch .LBB0_1483

.Lmla_ld_issue:
	global_load_dwordx4 v[24:27], v[24:25], off
	s_nop 0
	global_load_dwordx4 v[28:31], v[28:29], off
	s_nop 0
	global_load_dwordx4 v[32:35], v[32:33], off
	s_nop 0
	global_load_dwordx4 v[36:39], v[36:37], off
	s_nop 0
	global_load_dwordx4 v[40:43], v[40:41], off
	s_nop 0
	global_load_dwordx4 v[48:51], v[48:49], off
	s_nop 0
	global_load_dwordx4 v[52:55], v[56:57], off offset:128
	s_nop 0
	global_load_dwordx4 v[56:59], v[56:57], off offset:192
	s_nop 0
	global_load_dwordx4 v[60:63], v[64:65], off offset:128
	s_nop 0
	global_load_dwordx4 v[64:67], v[64:65], off offset:192
	s_barrier
	s_branch .LBB0_1483
